# adaLN dot-product loop (phase 0): 32 weight rows in flight per trip instead of 8, same fma order
# baseline (speedup 1.0000x reference)
.LBB0_1359:
	v_lshl_add_u64 v[50:51], v[4:5], 0, s[2:3]
	global_load_dword v34, v[50:51], off
	v_add_co_u32_e64 v50, s[40:41], s95, v50
	s_nop 1
	v_addc_co_u32_e64 v51, s[40:41], 0, v51, s[40:41]
	global_load_dword v35, v[50:51], off
	v_add_co_u32_e64 v50, s[40:41], s95, v50
	s_nop 1
	v_addc_co_u32_e64 v51, s[40:41], 0, v51, s[40:41]
	global_load_dword v36, v[50:51], off
	v_add_co_u32_e64 v50, s[40:41], s95, v50
	s_nop 1
	v_addc_co_u32_e64 v51, s[40:41], 0, v51, s[40:41]
	global_load_dword v37, v[50:51], off
	v_add_co_u32_e64 v50, s[40:41], s95, v50
	s_nop 1
	v_addc_co_u32_e64 v51, s[40:41], 0, v51, s[40:41]
	global_load_dword v38, v[50:51], off
	v_add_co_u32_e64 v50, s[40:41], s95, v50
	s_nop 1
	v_addc_co_u32_e64 v51, s[40:41], 0, v51, s[40:41]
	global_load_dword v39, v[50:51], off
	v_add_co_u32_e64 v50, s[40:41], s95, v50
	s_nop 1
	v_addc_co_u32_e64 v51, s[40:41], 0, v51, s[40:41]
	global_load_dword v40, v[50:51], off
	v_add_co_u32_e64 v50, s[40:41], s95, v50
	s_nop 1
	v_addc_co_u32_e64 v51, s[40:41], 0, v51, s[40:41]
	global_load_dword v41, v[50:51], off
	v_add_co_u32_e64 v50, s[40:41], s95, v50
	s_nop 1
	v_addc_co_u32_e64 v51, s[40:41], 0, v51, s[40:41]
	global_load_dword v42, v[50:51], off
	v_add_co_u32_e64 v50, s[40:41], s95, v50
	s_nop 1
	v_addc_co_u32_e64 v51, s[40:41], 0, v51, s[40:41]
	global_load_dword v43, v[50:51], off
	v_add_co_u32_e64 v50, s[40:41], s95, v50
	s_nop 1
	v_addc_co_u32_e64 v51, s[40:41], 0, v51, s[40:41]
	global_load_dword v44, v[50:51], off
	v_add_co_u32_e64 v50, s[40:41], s95, v50
	s_nop 1
	v_addc_co_u32_e64 v51, s[40:41], 0, v51, s[40:41]
	global_load_dword v45, v[50:51], off
	v_add_co_u32_e64 v50, s[40:41], s95, v50
	s_nop 1
	v_addc_co_u32_e64 v51, s[40:41], 0, v51, s[40:41]
	global_load_dword v46, v[50:51], off
	v_add_co_u32_e64 v50, s[40:41], s95, v50
	s_nop 1
	v_addc_co_u32_e64 v51, s[40:41], 0, v51, s[40:41]
	global_load_dword v47, v[50:51], off
	v_add_co_u32_e64 v50, s[40:41], s95, v50
	s_nop 1
	v_addc_co_u32_e64 v51, s[40:41], 0, v51, s[40:41]
	global_load_dword v48, v[50:51], off
	v_add_co_u32_e64 v50, s[40:41], s95, v50
	s_nop 1
	v_addc_co_u32_e64 v51, s[40:41], 0, v51, s[40:41]
	global_load_dword v49, v[50:51], off
	v_add_co_u32_e64 v50, s[40:41], s95, v50
	s_nop 1
	v_addc_co_u32_e64 v51, s[40:41], 0, v51, s[40:41]
	global_load_dword v52, v[50:51], off
	v_add_co_u32_e64 v50, s[40:41], s95, v50
	s_nop 1
	v_addc_co_u32_e64 v51, s[40:41], 0, v51, s[40:41]
	global_load_dword v53, v[50:51], off
	v_add_co_u32_e64 v50, s[40:41], s95, v50
	s_nop 1
	v_addc_co_u32_e64 v51, s[40:41], 0, v51, s[40:41]
	global_load_dword v54, v[50:51], off
	v_add_co_u32_e64 v50, s[40:41], s95, v50
	s_nop 1
	v_addc_co_u32_e64 v51, s[40:41], 0, v51, s[40:41]
	global_load_dword v55, v[50:51], off
	v_add_co_u32_e64 v50, s[40:41], s95, v50
	s_nop 1
	v_addc_co_u32_e64 v51, s[40:41], 0, v51, s[40:41]
	global_load_dword v56, v[50:51], off
	v_add_co_u32_e64 v50, s[40:41], s95, v50
	s_nop 1
	v_addc_co_u32_e64 v51, s[40:41], 0, v51, s[40:41]
	global_load_dword v57, v[50:51], off
	v_add_co_u32_e64 v50, s[40:41], s95, v50
	s_nop 1
	v_addc_co_u32_e64 v51, s[40:41], 0, v51, s[40:41]
	global_load_dword v58, v[50:51], off
	v_add_co_u32_e64 v50, s[40:41], s95, v50
	s_nop 1
	v_addc_co_u32_e64 v51, s[40:41], 0, v51, s[40:41]
	global_load_dword v59, v[50:51], off
	v_add_co_u32_e64 v50, s[40:41], s95, v50
	s_nop 1
	v_addc_co_u32_e64 v51, s[40:41], 0, v51, s[40:41]
	global_load_dword v60, v[50:51], off
	v_add_co_u32_e64 v50, s[40:41], s95, v50
	s_nop 1
	v_addc_co_u32_e64 v51, s[40:41], 0, v51, s[40:41]
	global_load_dword v61, v[50:51], off
	v_add_co_u32_e64 v50, s[40:41], s95, v50
	s_nop 1
	v_addc_co_u32_e64 v51, s[40:41], 0, v51, s[40:41]
	global_load_dword v62, v[50:51], off
	v_add_co_u32_e64 v50, s[40:41], s95, v50
	s_nop 1
	v_addc_co_u32_e64 v51, s[40:41], 0, v51, s[40:41]
	global_load_dword v63, v[50:51], off
	v_add_co_u32_e64 v50, s[40:41], s95, v50
	s_nop 1
	v_addc_co_u32_e64 v51, s[40:41], 0, v51, s[40:41]
	global_load_dword v64, v[50:51], off
	v_add_co_u32_e64 v50, s[40:41], s95, v50
	s_nop 1
	v_addc_co_u32_e64 v51, s[40:41], 0, v51, s[40:41]
	global_load_dword v65, v[50:51], off
	v_add_co_u32_e64 v50, s[40:41], s95, v50
	s_nop 1
	v_addc_co_u32_e64 v51, s[40:41], 0, v51, s[40:41]
	global_load_dword v66, v[50:51], off
	v_add_co_u32_e64 v50, s[40:41], s95, v50
	s_nop 1
	v_addc_co_u32_e64 v51, s[40:41], 0, v51, s[40:41]
	global_load_dword v67, v[50:51], off
	v_mov_b32_e32 v68, s1
	s_add_u32 s2, s2, 0xc0000
	s_addc_u32 s3, s3, 0
	s_addk_i32 s1, 0x80
	ds_read_b128 v[10:13], v68 offset:0
	ds_read_b128 v[14:17], v68 offset:16
	ds_read_b128 v[18:21], v68 offset:4096
	ds_read_b128 v[22:25], v68 offset:4112
	ds_read_b128 v[26:29], v68 offset:8192
	ds_read_b128 v[30:33], v68 offset:8208
	s_waitcnt lgkmcnt(0)
	s_waitcnt vmcnt(31)
	v_fmac_f32_e32 v6, v34, v10
	v_fmac_f32_e32 v7, v34, v18
	v_fmac_f32_e32 v9, v34, v26
	s_waitcnt vmcnt(30)
	v_fmac_f32_e32 v6, v35, v11
	v_fmac_f32_e32 v7, v35, v19
	v_fmac_f32_e32 v9, v35, v27
	s_waitcnt vmcnt(29)
	v_fmac_f32_e32 v6, v36, v12
	v_fmac_f32_e32 v7, v36, v20
	v_fmac_f32_e32 v9, v36, v28
	s_waitcnt vmcnt(28)
	v_fmac_f32_e32 v6, v37, v13
	v_fmac_f32_e32 v7, v37, v21
	v_fmac_f32_e32 v9, v37, v29
	s_waitcnt vmcnt(27)
	v_fmac_f32_e32 v6, v38, v14
	v_fmac_f32_e32 v7, v38, v22
	v_fmac_f32_e32 v9, v38, v30
	s_waitcnt vmcnt(26)
	v_fmac_f32_e32 v6, v39, v15
	v_fmac_f32_e32 v7, v39, v23
	v_fmac_f32_e32 v9, v39, v31
	s_waitcnt vmcnt(25)
	v_fmac_f32_e32 v6, v40, v16
	v_fmac_f32_e32 v7, v40, v24
	v_fmac_f32_e32 v9, v40, v32
	s_waitcnt vmcnt(24)
	v_fmac_f32_e32 v6, v41, v17
	v_fmac_f32_e32 v7, v41, v25
	v_fmac_f32_e32 v9, v41, v33
	ds_read_b128 v[10:13], v68 offset:32
	ds_read_b128 v[14:17], v68 offset:48
	ds_read_b128 v[18:21], v68 offset:4128
	ds_read_b128 v[22:25], v68 offset:4144
	ds_read_b128 v[26:29], v68 offset:8224
	ds_read_b128 v[30:33], v68 offset:8240
	s_waitcnt lgkmcnt(0)
	s_waitcnt vmcnt(23)
	v_fmac_f32_e32 v6, v42, v10
	v_fmac_f32_e32 v7, v42, v18
	v_fmac_f32_e32 v9, v42, v26
	s_waitcnt vmcnt(22)
	v_fmac_f32_e32 v6, v43, v11
	v_fmac_f32_e32 v7, v43, v19
	v_fmac_f32_e32 v9, v43, v27
	s_waitcnt vmcnt(21)
	v_fmac_f32_e32 v6, v44, v12
	v_fmac_f32_e32 v7, v44, v20
	v_fmac_f32_e32 v9, v44, v28
	s_waitcnt vmcnt(20)
	v_fmac_f32_e32 v6, v45, v13
	v_fmac_f32_e32 v7, v45, v21
	v_fmac_f32_e32 v9, v45, v29
	s_waitcnt vmcnt(19)
	v_fmac_f32_e32 v6, v46, v14
	v_fmac_f32_e32 v7, v46, v22
	v_fmac_f32_e32 v9, v46, v30
	s_waitcnt vmcnt(18)
	v_fmac_f32_e32 v6, v47, v15
	v_fmac_f32_e32 v7, v47, v23
	v_fmac_f32_e32 v9, v47, v31
	s_waitcnt vmcnt(17)
	v_fmac_f32_e32 v6, v48, v16
	v_fmac_f32_e32 v7, v48, v24
	v_fmac_f32_e32 v9, v48, v32
	s_waitcnt vmcnt(16)
	v_fmac_f32_e32 v6, v49, v17
	v_fmac_f32_e32 v7, v49, v25
	v_fmac_f32_e32 v9, v49, v33
	ds_read_b128 v[10:13], v68 offset:64
	ds_read_b128 v[14:17], v68 offset:80
	ds_read_b128 v[18:21], v68 offset:4160
	ds_read_b128 v[22:25], v68 offset:4176
	ds_read_b128 v[26:29], v68 offset:8256
	ds_read_b128 v[30:33], v68 offset:8272
	s_waitcnt lgkmcnt(0)
	s_waitcnt vmcnt(15)
	v_fmac_f32_e32 v6, v52, v10
	v_fmac_f32_e32 v7, v52, v18
	v_fmac_f32_e32 v9, v52, v26
	s_waitcnt vmcnt(14)
	v_fmac_f32_e32 v6, v53, v11
	v_fmac_f32_e32 v7, v53, v19
	v_fmac_f32_e32 v9, v53, v27
	s_waitcnt vmcnt(13)
	v_fmac_f32_e32 v6, v54, v12
	v_fmac_f32_e32 v7, v54, v20
	v_fmac_f32_e32 v9, v54, v28
	s_waitcnt vmcnt(12)
	v_fmac_f32_e32 v6, v55, v13
	v_fmac_f32_e32 v7, v55, v21
	v_fmac_f32_e32 v9, v55, v29
	s_waitcnt vmcnt(11)
	v_fmac_f32_e32 v6, v56, v14
	v_fmac_f32_e32 v7, v56, v22
	v_fmac_f32_e32 v9, v56, v30
	s_waitcnt vmcnt(10)
	v_fmac_f32_e32 v6, v57, v15
	v_fmac_f32_e32 v7, v57, v23
	v_fmac_f32_e32 v9, v57, v31
	s_waitcnt vmcnt(9)
	v_fmac_f32_e32 v6, v58, v16
	v_fmac_f32_e32 v7, v58, v24
	v_fmac_f32_e32 v9, v58, v32
	s_waitcnt vmcnt(8)
	v_fmac_f32_e32 v6, v59, v17
	v_fmac_f32_e32 v7, v59, v25
	v_fmac_f32_e32 v9, v59, v33
	ds_read_b128 v[10:13], v68 offset:96
	ds_read_b128 v[14:17], v68 offset:112
	ds_read_b128 v[18:21], v68 offset:4192
	ds_read_b128 v[22:25], v68 offset:4208
	ds_read_b128 v[26:29], v68 offset:8288
	ds_read_b128 v[30:33], v68 offset:8304
	s_waitcnt lgkmcnt(0)
	s_waitcnt vmcnt(7)
	v_fmac_f32_e32 v6, v60, v10
	v_fmac_f32_e32 v7, v60, v18
	v_fmac_f32_e32 v9, v60, v26
	s_waitcnt vmcnt(6)
	v_fmac_f32_e32 v6, v61, v11
	v_fmac_f32_e32 v7, v61, v19
	v_fmac_f32_e32 v9, v61, v27
	s_waitcnt vmcnt(5)
	v_fmac_f32_e32 v6, v62, v12
	v_fmac_f32_e32 v7, v62, v20
	v_fmac_f32_e32 v9, v62, v28
	s_waitcnt vmcnt(4)
	v_fmac_f32_e32 v6, v63, v13
	v_fmac_f32_e32 v7, v63, v21
	v_fmac_f32_e32 v9, v63, v29
	s_waitcnt vmcnt(3)
	v_fmac_f32_e32 v6, v64, v14
	v_fmac_f32_e32 v7, v64, v22
	v_fmac_f32_e32 v9, v64, v30
	s_waitcnt vmcnt(2)
	v_fmac_f32_e32 v6, v65, v15
	v_fmac_f32_e32 v7, v65, v23
	v_fmac_f32_e32 v9, v65, v31
	s_waitcnt vmcnt(1)
	v_fmac_f32_e32 v6, v66, v16
	v_fmac_f32_e32 v7, v66, v24
	v_fmac_f32_e32 v9, v66, v32
	s_waitcnt vmcnt(0)
	v_fmac_f32_e32 v6, v67, v17
	v_fmac_f32_e32 v7, v67, v25
	v_fmac_f32_e32 v9, v67, v33
	s_cmp_eq_u32 s2, 0x300000
	s_cbranch_scc0 .LBB0_1359
	ds_write2st64_b32 v8, v6, v7 offset0:64 offset1:65
	ds_write_b32 v8, v9 offset:16896
	s_waitcnt lgkmcnt(0)
	s_barrier
	s_and_saveexec_b64 s[2:3], vcc
	s_cbranch_execz .LBB0_1357
	s_load_dwordx2 s[8:9], s[42:43], 0x28
	s_mul_i32 s1, s6, 0x1800
	s_add_i32 s1, s1, s0
	v_or_b32_e32 v4, s1, v223
	v_ashrrev_i32_e32 v5, 31, v4
	s_waitcnt lgkmcnt(0)
	v_lshl_add_u64 v[4:5], v[4:5], 2, s[8:9]
	global_load_dword v9, v[4:5], off
	ds_read2st64_b32 v[4:5], v0 offset0:64 offset1:67
	ds_read2st64_b32 v[6:7], v0 offset0:70 offset1:73
	ds_read2st64_b32 v[10:11], v0 offset0:76 offset1:79
	ds_read2st64_b32 v[12:13], v0 offset0:82 offset1:85
	v_mad_u64_u32 v[14:15], s[6:7], s6, 3, v[190:191]
	s_waitcnt lgkmcnt(3)
	v_add_f32_e32 v4, 0, v4
	v_add_f32_e32 v4, v4, v5
	s_waitcnt lgkmcnt(2)
	v_add_f32_e32 v4, v4, v6
	v_add_f32_e32 v4, v4, v7
	v_mul_lo_u32 v14, v14, s90
	s_waitcnt lgkmcnt(1)
	v_add_f32_e32 v4, v4, v10
	v_add_u32_e32 v14, s0, v14
	v_add_f32_e32 v4, v4, v11
	v_or_b32_e32 v14, v14, v223
	s_waitcnt lgkmcnt(0)
	v_add_f32_e32 v4, v4, v12
	v_readlane_b32 s0, v254, 2
	v_ashrrev_i32_e32 v15, 31, v14
	v_add_f32_e32 v4, v4, v13
	v_readlane_b32 s1, v254, 3
	s_waitcnt vmcnt(0)
	v_add_f32_e32 v6, v4, v9
	v_lshl_add_u64 v[4:5], v[14:15], 2, s[0:1]
	global_store_dword v[4:5], v6, off
	s_branch .LBB0_1357
